# v61 + static priority raise (s_setprio 3) for the scan waves over their chunk loop
# speedup vs baseline: 1.0048x; 1.0048x over previous
.Lw_fwd:
	global_load_dwordx4 v[192:195], v118, s[56:57]
	s_add_u32 s56, s56, s58
	s_addc_u32 s57, s57, s59
	global_load_dwordx4 v[196:199], v118, s[56:57]
	s_add_u32 s56, s56, s58
	s_addc_u32 s57, s57, s59
	global_load_dwordx4 v[200:203], v118, s[56:57]
	s_add_u32 s56, s56, s58
	s_addc_u32 s57, s57, s59
	global_load_dwordx4 v[204:207], v118, s[56:57]
	s_add_u32 s56, s56, s58
	s_addc_u32 s57, s57, s59
	s_setprio 3
	ds_read_b128 v[224:227], v118
	ds_read_b128 v[228:231], v118 offset:512
	ds_read_b128 v[232:235], v118 offset:768
	ds_read_b128 v[236:239], v118 offset:1024
	s_waitcnt lgkmcnt(0)

.LBB0_834:
	s_setprio 0
	s_andn2_b64 vcc, exec, s[24:25]
	s_cbranch_vccnz .LBB0_706
	s_waitcnt vmcnt(6)
	v_ashrrev_i32_e32 v18, 5, v164
	v_lshlrev_b32_e32 v2, 11, v18
	v_add3_u32 v2, s70, v2, v119
	v_add3_u32 v14, v2, v123, v129
	ds_read_b128 v[2:5], v14
	ds_read_b128 v[6:9], v14 offset:16
	ds_read_b128 v[10:13], v14 offset:32
	ds_read_b128 v[14:17], v14 offset:48
	s_ashr_i32 s23, s22, 31
	s_lshl_b64 s[4:5], s[22:23], 2
	s_waitcnt lgkmcnt(2)
	v_pk_add_f32 v[4:5], v[4:5], v[8:9]
	v_pk_add_f32 v[2:3], v[2:3], v[6:7]
	s_waitcnt lgkmcnt(0)
	v_pk_add_f32 v[6:7], v[12:13], v[16:17]
	v_pk_add_f32 v[8:9], v[10:11], v[14:15]
	v_pk_add_f32 v[4:5], v[4:5], v[6:7]
	v_pk_add_f32 v[2:3], v[2:3], v[8:9]
	v_mov_b32_e32 v117, v115
	v_add_f32_e32 v2, v2, v3
	v_add_f32_e32 v3, v4, v5
	v_add_f32_e32 v20, v2, v3
	v_sub_u32_e32 v2, 15, v18
	v_add_u32_e32 v3, 0x1ff0, v18
	v_cndmask_b32_e64 v2, v2, v3, s[0:1]
	v_ashrrev_i32_e32 v3, 31, v2
	v_lshlrev_b64 v[2:3], 13, v[2:3]
	v_lshl_add_u64 v[2:3], s[26:27], 0, v[2:3]
	v_lshl_add_u64 v[18:19], v[2:3], 0, s[4:5]
	v_add_u32_e32 v2, 0x100, v164
	v_ashrrev_i32_e32 v21, 5, v2
	v_lshlrev_b32_e32 v2, 11, v21
	v_add3_u32 v2, s70, v2, v119
	v_add3_u32 v14, v2, v123, v129
	ds_read_b128 v[2:5], v14
	ds_read_b128 v[6:9], v14 offset:16
	ds_read_b128 v[10:13], v14 offset:32
	ds_read_b128 v[14:17], v14 offset:48
	v_lshl_add_u64 v[18:19], v[18:19], 0, v[116:117]
	global_store_dword v[18:19], v20, off
	s_waitcnt lgkmcnt(2)
	v_pk_add_f32 v[4:5], v[4:5], v[8:9]
	v_pk_add_f32 v[2:3], v[2:3], v[6:7]
	s_waitcnt lgkmcnt(0)
	v_pk_add_f32 v[6:7], v[12:13], v[16:17]
	v_pk_add_f32 v[8:9], v[10:11], v[14:15]
	v_pk_add_f32 v[4:5], v[4:5], v[6:7]
	v_pk_add_f32 v[2:3], v[2:3], v[8:9]
	s_nop 0
	v_add_f32_e32 v2, v2, v3
	v_add_f32_e32 v3, v4, v5
	v_add_f32_e32 v4, v2, v3
	v_sub_u32_e32 v2, 15, v21
	v_add_u32_e32 v3, 0x1ff0, v21
	v_cndmask_b32_e64 v2, v2, v3, s[0:1]
	v_ashrrev_i32_e32 v3, 31, v2
	v_lshlrev_b64 v[2:3], 13, v[2:3]
	v_lshl_add_u64 v[2:3], s[26:27], 0, v[2:3]
	v_lshl_add_u64 v[2:3], v[2:3], 0, s[4:5]
	v_lshl_add_u64 v[2:3], v[2:3], 0, v[116:117]
	global_store_dword v[2:3], v4, off
	s_branch .LBB0_706
